# v82 + phase-4 lag with x-tile prefetch (64 MB) by the sleeping workgroups
# baseline (speedup 1.0000x reference)
.LBB0_589:
	s_cmp_gt_i32 s26, 4
	s_cselect_b64 s[4:5], -1, 0
	s_xor_b64 s[0:1], s[0:1], -1
	s_or_b64 s[0:1], s[4:5], s[0:1]
	s_and_b64 vcc, exec, s[0:1]
	s_cbranch_vccnz .LBB0_771
	s_cmpk_lt_u32 s96, 0x80
	s_cbranch_scc1 .Lp4_lag
	s_sleep 127
	s_and_b32 s98, s96, 7
	s_lshl_b32 s98, s98, 3
	s_bfe_u32 s99, s96, 0x30003
	s_or_b32 s98, s98, s99
	s_lshl_b32 s98, s98, 20
	s_bfe_u32 s99, s96, 0x10006
	s_lshl_b32 s99, s99, 10
	s_or_b32 s98, s98, s99
	v_readlane_b32 s100, v254, 5
	v_readlane_b32 s101, v254, 6
	s_add_u32 s100, s100, s98
	s_addc_u32 s101, s101, 0
	v_and_b32_e32 v152, 0x3ff, v0
	v_lshrrev_b32_e32 v153, 1, v152
	v_and_b32_e32 v152, 1, v152
	v_lshlrev_b32_e32 v152, 9, v152
	v_lshl_or_b32 v153, v153, 12, v152
	s_nop 4
	global_load_dword v154, v153, s[100:101]
	global_load_dword v155, v153, s[100:101] offset:128
	s_sleep 60
	global_load_dword v156, v153, s[100:101] offset:256
	global_load_dword v157, v153, s[100:101] offset:384
	s_sleep 60
	global_load_dword v158, v153, s[100:101] offset:2048
	global_load_dword v159, v153, s[100:101] offset:2176
	s_sleep 60
	global_load_dword v160, v153, s[100:101] offset:2304
	global_load_dword v161, v153, s[100:101] offset:2432
	s_sleep 70
	s_waitcnt vmcnt(0)
